# v44 + nt on the KV-sum pass's K/V LDS-DMA loads
# speedup vs baseline: 1.0220x; 1.0220x over previous
.LBB0_318:
	v_readlane_b32 s0, v251, 20
	s_ashr_i32 s4, s0, 2
	s_and_b32 s81, s4, -4
	s_add_i32 s81, s81, s91
	s_lshl_b32 s10, s81, 4
	s_and_b32 s11, s0, 15
	s_ashr_i32 s60, s81, 2
	s_or_b32 s4, s10, s11
	s_and_b32 s95, s91, 3
	s_ashr_i32 s61, s60, 31
	s_add_u32 s59, s54, 0x4c00000
	s_addc_u32 s82, s55, 0
	s_lshl_b64 s[6:7], s[60:61], 23
	s_lshl_b32 s5, s11, 19
	v_cvt_f32_ubyte0_e32 v0, s95
	s_or_b32 s5, s6, s5
	v_sub_f32_e32 v0, 0xc0a00000, v0
	s_mov_b32 s6, 0xc2fc0000
	v_mov_b32_e32 v1, 0x42800000
	v_cmp_gt_f32_e32 vcc, s6, v0
	s_add_u32 s28, s59, s5
	s_addc_u32 s29, s82, s7
	v_cndmask_b32_e32 v1, 0, v1, vcc
	v_add_f32_e32 v0, v0, v1
	v_exp_f32_e32 v0, v0
	s_and_b64 s[8:9], vcc, exec
	s_cselect_b32 s6, 0xffffffc0, 0
	s_add_u32 s76, s54, 0x2c00000
	v_ldexp_f32 v0, v0, s6
	v_sub_f32_e32 v0, 1.0, v0
	s_mov_b32 s6, 0x800000
	s_addc_u32 s18, s55, 0
	v_cmp_gt_f32_e32 vcc, s6, v0
	s_and_b64 s[8:9], vcc, exec
	s_cselect_b32 s6, 32, 0
	s_add_u32 s5, s76, s5
	v_ldexp_f32 v0, v0, s6
	s_addc_u32 s38, s18, s7
	s_mul_i32 s39, s62, 3
	s_lshl_b32 s6, s95, 2
	s_lshl_b32 s40, s95, 3
	s_or_b32 s41, s6, 16
	s_add_i32 s8, s39, -16
	s_cmpk_gt_u32 s96, 0x17f
	s_cselect_b64 s[74:75], -1, 0
	s_and_b64 s[6:7], s[74:75], exec
	s_cselect_b32 s6, s8, s39
	s_cselect_b32 s7, s41, s40
	s_cselect_b32 s8, s38, s29
	s_cselect_b32 s9, s5, s28
	s_cselect_b32 s33, 0, 0x2000
	s_ashr_i32 s22, s6, 1
	s_and_b32 s23, s6, 1
	s_add_i32 s6, s7, s22
	v_readlane_b32 s1, v251, 21
	s_ashr_i32 s7, s6, 31
	s_lshl_b32 s77, s23, 9
	s_lshl_b64 s[0:1], s[6:7], 14
	s_add_u32 s6, s9, s0
	s_addc_u32 s7, s8, s1
	s_lshl_b32 s34, s22, 11
	s_lshl_b32 s35, s23, 10
	s_cmpk_gt_u32 s96, 0x13f
	s_cselect_b64 s[84:85], -1, 0
	s_and_b64 s[8:9], s[84:85], exec
	v_log_f32_e32 v0, v0
	s_cselect_b32 s8, -15, 1
	s_cselect_b32 s40, s41, s40
	s_cselect_b32 s5, s5, s28
	s_cselect_b32 s41, s38, s29
	s_cselect_b32 s56, 0, 0x2000
	s_cselect_b32 s38, -14, 2
	s_add_i32 s8, s8, s39
	v_mov_b32_e32 v1, 0x42000000
	s_ashr_i32 s42, s8, 1
	v_cndmask_b32_e32 v1, 0, v1, vcc
	s_and_b32 s43, s8, 1
	s_add_i32 s8, s40, s42
	v_sub_f32_e32 v174, v0, v1
	s_ashr_i32 s9, s8, 31
	v_mul_f32_e32 v0, 0x80000000, v174
	s_lshl_b32 s78, s43, 9
	s_lshl_b64 s[28:29], s[8:9], 14
	v_exp_f32_e32 v70, v0
	v_mul_f32_e32 v0, -2.0, v174
	s_add_u32 s8, s5, s28
	v_exp_f32_e32 v68, v0
	v_mul_f32_e32 v0, 0xc0400000, v174
	s_addc_u32 s9, s41, s29
	s_add_i32 s38, s38, s39
	v_exp_f32_e32 v69, v0
	v_mul_f32_e32 v0, 0xc1000000, v174
	s_lshl_b32 s57, s42, 11
	s_ashr_i32 s42, s38, 1
	v_exp_f32_e32 v66, v0
	v_mul_f32_e32 v0, 0xc1100000, v174
	s_add_i32 s38, s40, s42
	v_exp_f32_e32 v67, v0
	v_mul_f32_e32 v0, 0xc1200000, v174
	s_lshl_b32 s64, s43, 10
	s_and_b32 s43, s39, 1
	s_ashr_i32 s39, s38, 31
	s_barrier
	v_exp_f32_e32 v64, v0
	v_mul_f32_e32 v0, 0xc1300000, v174
	s_lshl_b32 s79, s43, 9
	s_lshl_b64 s[38:39], s[38:39], 14
	v_mbcnt_lo_u32_b32 v72, -1, 0
	v_mbcnt_hi_u32_b32 v72, -1, v72
	v_exp_f32_e32 v65, v0
	v_ashrrev_i32_e32 v73, 5, v72
	s_add_u32 s40, s5, s38
	v_lshlrev_b32_e32 v74, 2, v73
	v_lshrrev_b32_e32 v0, 2, v72
	s_addc_u32 s41, s41, s39
	s_add_i32 s5, s33, 0
	v_and_or_b32 v0, v0, 3, v74
	v_lshlrev_b32_e32 v75, 3, v72
	s_add_i32 s69, s5, s34
	v_lshlrev_b32_e32 v1, 1, v72
	v_lshlrev_b32_e32 v4, 6, v0
	v_add_u32_e32 v0, s77, v75
	s_add_i32 s69, s69, s35
	v_and_b32_e32 v2, 32, v1
	v_ashrrev_i32_e32 v1, 31, v0
	s_add_i32 s5, s56, 0
	v_lshl_add_u64 v[0:1], v[0:1], 1, s[6:7]
	s_mov_b32 m0, s69
	s_add_i32 s68, s5, s57
	global_load_lds_dwordx4 v[0:1], off nt
	v_add_u32_e32 v0, s78, v75
	s_add_i32 s68, s68, s64
	v_ashrrev_i32_e32 v1, 31, v0
	s_lshl_b32 s65, s42, 11
	v_lshl_add_u64 v[0:1], v[0:1], 1, s[8:9]
	s_mov_b32 m0, s68
	s_lshl_b32 s80, s43, 10
	s_add_i32 s67, s5, s65
	global_load_lds_dwordx4 v[0:1], off nt
	v_add_u32_e32 v0, s79, v75
	s_add_i32 s67, s67, s80
	v_ashrrev_i32_e32 v1, 31, v0
	v_lshl_add_u64 v[0:1], v[0:1], 1, s[40:41]
	s_mov_b32 m0, s67
	v_add_u32_e32 v5, 0x400, v75
	global_load_lds_dwordx4 v[0:1], off nt
	v_add_u32_e32 v0, s77, v5
	s_add_i32 s66, s69, 0x6000
	v_ashrrev_i32_e32 v1, 31, v0
	v_lshl_add_u64 v[0:1], v[0:1], 1, s[6:7]
	s_mov_b32 m0, s66
	s_add_i32 s49, s68, 0x6000
	global_load_lds_dwordx4 v[0:1], off nt
	v_add_u32_e32 v0, s78, v5
	v_ashrrev_i32_e32 v1, 31, v0
	v_lshl_add_u64 v[0:1], v[0:1], 1, s[8:9]
	s_mov_b32 m0, s49
	s_add_i32 s48, s67, 0x6000
	global_load_lds_dwordx4 v[0:1], off nt
	v_add_u32_e32 v0, s79, v5
	v_ashrrev_i32_e32 v1, 31, v0
	v_lshl_add_u64 v[0:1], v[0:1], 1, s[40:41]
	s_mov_b32 m0, s48
	v_add_u32_e32 v5, 0x800, v75
	global_load_lds_dwordx4 v[0:1], off nt
	v_add_u32_e32 v0, s77, v5
	s_add_i32 s46, s69, 0xc000
	v_ashrrev_i32_e32 v1, 31, v0
	v_lshl_add_u64 v[0:1], v[0:1], 1, s[6:7]
	s_mov_b32 m0, s46
	s_add_i32 s45, s68, 0xc000
	global_load_lds_dwordx4 v[0:1], off nt
	v_add_u32_e32 v0, s78, v5
	v_ashrrev_i32_e32 v1, 31, v0
	v_lshl_add_u64 v[0:1], v[0:1], 1, s[8:9]
	s_mov_b32 m0, s45
	s_add_i32 s44, s67, 0xc000
	global_load_lds_dwordx4 v[0:1], off nt
	v_add_u32_e32 v0, s79, v5
	s_add_i32 s72, 0, 0x12000
	v_and_b32_e32 v3, 24, v75
	v_ashrrev_i32_e32 v1, 31, v0
	s_add_i32 s5, s72, s33
	v_lshl_add_u64 v[0:1], v[0:1], 1, s[40:41]
	s_mov_b32 m0, s44
	v_or3_b32 v106, v4, v2, v3
	v_add_u32_e32 v2, 0xc00, v75
	s_add_i32 s43, s5, s34
	global_load_lds_dwordx4 v[0:1], off nt
	v_add_u32_e32 v0, s77, v2
	s_add_i32 s43, s43, s35
	v_ashrrev_i32_e32 v1, 31, v0
	s_add_i32 s5, s72, s56
	s_waitcnt vmcnt(6)
	s_barrier
	v_lshl_add_u64 v[0:1], v[0:1], 1, s[6:7]
	s_mov_b32 m0, s43
	s_add_i32 s42, s5, s57
	global_load_lds_dwordx4 v[0:1], off nt
	v_add_u32_e32 v0, s78, v2
	s_add_i32 s42, s42, s64
	v_ashrrev_i32_e32 v1, 31, v0
	v_lshl_add_u64 v[0:1], v[0:1], 1, s[8:9]
	s_mov_b32 m0, s42
	s_add_i32 s5, s5, s65
	global_load_lds_dwordx4 v[0:1], off nt
	v_add_u32_e32 v0, s79, v2
	s_lshl_b32 s47, s62, 11
	s_add_i32 s5, s5, s80
	v_ashrrev_i32_e32 v1, 31, v0
	s_add_i32 s47, s47, 0
	v_lshl_add_u64 v[0:1], v[0:1], 1, s[40:41]
	s_mov_b32 m0, s5
	v_add_u32_e32 v107, s47, v106
	global_load_lds_dwordx4 v[0:1], off nt
	v_add_u32_e32 v77, 0x2000, v107
	ds_read_b64_tr_b16 v[16:17], v77
	ds_read_b64_tr_b16 v[18:19], v77 offset:512
	v_sub_u32_e32 v20, 0xff, v74
	v_add_u32_e32 v78, 0, v106
	ds_read_b64_tr_b16 v[0:1], v78
	ds_read_b64_tr_b16 v[2:3], v78 offset:512
	v_cvt_f32_i32_e32 v20, v20
	v_add_u32_e32 v79, 0x800, v78
	ds_read_b64_tr_b16 v[4:5], v79
	ds_read_b64_tr_b16 v[6:7], v79 offset:512
	v_add_u32_e32 v80, 0x1000, v78
	ds_read_b64_tr_b16 v[8:9], v80
	ds_read_b64_tr_b16 v[10:11], v80 offset:512
	v_add_u32_e32 v81, 0x1800, v78
	ds_read_b64_tr_b16 v[12:13], v81
	ds_read_b64_tr_b16 v[14:15], v81 offset:512
	v_add_u32_e32 v82, 0x2400, v107
	ds_read_b64_tr_b16 v[108:109], v82
	ds_read_b64_tr_b16 v[110:111], v82 offset:512
	v_mul_f32_e32 v20, v174, v20
	v_exp_f32_e64 v71, -v174
	v_add_u32_e32 v83, 0x400, v78
	ds_read_b64_tr_b16 v[86:87], v83
	ds_read_b64_tr_b16 v[88:89], v83 offset:512
	v_exp_f32_e32 v20, v20
	v_add_u32_e32 v84, 0xc00, v78
	ds_read_b64_tr_b16 v[90:91], v84
	ds_read_b64_tr_b16 v[92:93], v84 offset:512
	v_add_u32_e32 v76, 0x1400, v78
	ds_read_b64_tr_b16 v[94:95], v76
	ds_read_b64_tr_b16 v[96:97], v76 offset:512
	v_add_u32_e32 v85, 0x1c00, v78
	ds_read_b64_tr_b16 v[98:99], v85
	ds_read_b64_tr_b16 v[100:101], v85 offset:512
	v_pk_mul_f32 v[24:25], v[70:71], v[20:21] op_sel_hi:[1,0]
	s_waitcnt lgkmcnt(0)
	s_waitcnt vmcnt(6)
	s_barrier
	v_lshlrev_b32_e32 v22, 16, v16
	v_and_b32_e32 v23, 0xffff0000, v16
	v_pk_mul_f32 v[22:23], v[24:25], v[22:23]
	v_lshlrev_b32_e32 v16, 16, v17
	v_cvt_pk_bf16_f32 v102, v22, v23
	v_and_b32_e32 v17, 0xffff0000, v17
	v_pk_mul_f32 v[22:23], v[68:69], v[20:21] op_sel_hi:[1,0]
	s_mov_b32 m0, s69
	v_pk_mul_f32 v[16:17], v[22:23], v[16:17]
	v_pk_mul_f32 v[22:23], v[66:67], v[20:21] op_sel_hi:[1,0]
	v_cvt_pk_bf16_f32 v103, v16, v17
	v_lshlrev_b32_e32 v16, 16, v18
	v_and_b32_e32 v17, 0xffff0000, v18
	v_pk_mul_f32 v[16:17], v[22:23], v[16:17]
	s_add_i32 s47, s47, 0x14000
	v_cvt_pk_bf16_f32 v104, v16, v17
	v_lshlrev_b32_e32 v16, 16, v19
	v_and_b32_e32 v17, 0xffff0000, v19
	v_pk_mul_f32 v[18:19], v[64:65], v[20:21] op_sel_hi:[1,0]
	s_nop 0
	v_pk_mul_f32 v[16:17], v[18:19], v[16:17]
	s_nop 0
	v_cvt_pk_bf16_f32 v105, v16, v17
	s_nop 1
	v_mfma_f32_32x32x16_bf16 v[48:63], v[0:3], v[102:105], 0
	v_sub_u32_e32 v0, 0xef, v74
	v_cvt_f32_i32_e32 v0, v0
	v_mul_f32_e32 v0, v174, v0
	v_exp_f32_e32 v112, v0
	v_mfma_f32_32x32x16_bf16 v[32:47], v[4:7], v[102:105], 0
	v_mfma_f32_32x32x16_bf16 v[16:31], v[8:11], v[102:105], 0
	v_mfma_f32_32x32x16_bf16 v[0:15], v[12:15], v[102:105], 0
	v_lshlrev_b32_e32 v102, 16, v108
	v_and_b32_e32 v103, 0xffff0000, v108
	v_mul_f32_e64 v104, v70, v112
	v_mul_f32_e64 v105, v71, v112
	v_mul_f32_e64 v102, v104, v102
	v_mul_f32_e64 v103, v105, v103
	v_lshlrev_b32_e32 v104, 16, v109
	v_and_b32_e32 v105, 0xffff0000, v109
	v_pk_mul_f32 v[108:109], v[68:69], v[112:113] op_sel_hi:[1,0]
	v_cvt_pk_bf16_f32 v102, v102, v103
	v_pk_mul_f32 v[104:105], v[108:109], v[104:105]
	v_pk_mul_f32 v[108:109], v[66:67], v[112:113] op_sel_hi:[1,0]
	v_cvt_pk_bf16_f32 v103, v104, v105
	v_lshlrev_b32_e32 v104, 16, v110
	v_and_b32_e32 v105, 0xffff0000, v110
	v_pk_mul_f32 v[104:105], v[108:109], v[104:105]
	v_lshlrev_b32_e32 v108, 16, v111
	v_and_b32_e32 v109, 0xffff0000, v111
	v_pk_mul_f32 v[110:111], v[64:65], v[112:113] op_sel_hi:[1,0]
	v_cvt_pk_bf16_f32 v104, v104, v105
	v_pk_mul_f32 v[108:109], v[110:111], v[108:109]
	s_nop 0
	v_cvt_pk_bf16_f32 v105, v108, v109
	s_nop 1
	v_mfma_f32_32x32x16_bf16 v[48:63], v[86:89], v[102:105], v[48:63]
	v_add_u32_e32 v88, 0x1000, v75
	v_add_u32_e32 v86, s77, v88
	v_ashrrev_i32_e32 v87, 31, v86
	v_lshl_add_u64 v[86:87], v[86:87], 1, s[6:7]
	global_load_lds_dwordx4 v[86:87], off nt
	v_add_u32_e32 v86, s78, v88
	v_ashrrev_i32_e32 v87, 31, v86
	v_lshl_add_u64 v[86:87], v[86:87], 1, s[8:9]
	s_mov_b32 m0, s68
	v_mfma_f32_32x32x16_bf16 v[32:47], v[90:93], v[102:105], v[32:47]
	global_load_lds_dwordx4 v[86:87], off nt
	v_add_u32_e32 v86, s79, v88
	v_ashrrev_i32_e32 v87, 31, v86
	v_lshl_add_u64 v[86:87], v[86:87], 1, s[40:41]
	s_mov_b32 m0, s67
	v_add_u32_e32 v88, 0x6000, v78
	global_load_lds_dwordx4 v[86:87], off nt
	v_mfma_f32_32x32x16_bf16 v[16:31], v[94:97], v[102:105], v[16:31]
	v_add_u32_e32 v87, 0x8000, v107
	v_sub_u32_e32 v95, 0xdf, v74
	v_cvt_f32_i32_e32 v132, v95
	v_add_u32_e32 v89, 0x6800, v78
	v_add_u32_e32 v90, 0x7000, v78
	v_add_u32_e32 v91, 0x7800, v78
	v_add_u32_e32 v92, 0x8400, v107
	v_mfma_f32_32x32x16_bf16 v[0:15], v[98:101], v[102:105], v[0:15]
	ds_read_b64_tr_b16 v[104:105], v87
	ds_read_b64_tr_b16 v[134:135], v87 offset:512
	ds_read_b64_tr_b16 v[96:97], v88
	ds_read_b64_tr_b16 v[98:99], v88 offset:512
	ds_read_b64_tr_b16 v[100:101], v89
	ds_read_b64_tr_b16 v[102:103], v89 offset:512
	ds_read_b64_tr_b16 v[108:109], v90
	ds_read_b64_tr_b16 v[110:111], v90 offset:512
	ds_read_b64_tr_b16 v[112:113], v91
	ds_read_b64_tr_b16 v[114:115], v91 offset:512
	ds_read_b64_tr_b16 v[136:137], v92
	ds_read_b64_tr_b16 v[138:139], v92 offset:512
	v_mul_f32_e32 v132, v174, v132
	v_add_u32_e32 v93, 0x6400, v78
	ds_read_b64_tr_b16 v[116:117], v93
	ds_read_b64_tr_b16 v[118:119], v93 offset:512
	v_exp_f32_e32 v140, v132
	v_add_u32_e32 v94, 0x6c00, v78
	ds_read_b64_tr_b16 v[120:121], v94
	ds_read_b64_tr_b16 v[122:123], v94 offset:512
	v_add_u32_e32 v86, 0x7400, v78
	ds_read_b64_tr_b16 v[124:125], v86
	ds_read_b64_tr_b16 v[126:127], v86 offset:512
	v_add_u32_e32 v95, 0x7c00, v78
	ds_read_b64_tr_b16 v[128:129], v95
	ds_read_b64_tr_b16 v[130:131], v95 offset:512
	v_pk_mul_f32 v[142:143], v[70:71], v[140:141] op_sel_hi:[1,0]
	s_waitcnt lgkmcnt(0)
	s_waitcnt vmcnt(6)
	s_barrier
	v_lshlrev_b32_e32 v132, 16, v104
	v_and_b32_e32 v133, 0xffff0000, v104
	v_pk_mul_f32 v[132:133], v[142:143], v[132:133]
	v_lshlrev_b32_e32 v104, 16, v105
	v_and_b32_e32 v105, 0xffff0000, v105
	v_pk_mul_f32 v[142:143], v[68:69], v[140:141] op_sel_hi:[1,0]
	v_cvt_pk_bf16_f32 v132, v132, v133
	v_pk_mul_f32 v[104:105], v[142:143], v[104:105]
	v_pk_mul_f32 v[142:143], v[66:67], v[140:141] op_sel_hi:[1,0]
	v_cvt_pk_bf16_f32 v133, v104, v105
	v_lshlrev_b32_e32 v104, 16, v134
	v_and_b32_e32 v105, 0xffff0000, v134
	v_pk_mul_f32 v[104:105], v[142:143], v[104:105]
	v_pk_mul_f32 v[140:141], v[64:65], v[140:141] op_sel_hi:[1,0]
	v_cvt_pk_bf16_f32 v134, v104, v105
	v_lshlrev_b32_e32 v104, 16, v135
	v_and_b32_e32 v105, 0xffff0000, v135
	v_pk_mul_f32 v[104:105], v[140:141], v[104:105]
	s_mov_b32 m0, s66
	v_cvt_pk_bf16_f32 v135, v104, v105
	v_sub_u32_e32 v105, 0xbf, v74
	v_add_u32_e32 v104, 0xcc00, v78
	v_mfma_f32_32x32x16_bf16 v[48:63], v[96:99], v[132:135], v[48:63]
	v_sub_u32_e32 v96, 0xcf, v74
	v_cvt_f32_i32_e32 v96, v96
	v_and_b32_e32 v97, 0xffff0000, v136
	v_mul_f32_e32 v96, v174, v96
	v_mfma_f32_32x32x16_bf16 v[32:47], v[100:103], v[132:135], v[32:47]
	v_exp_f32_e32 v100, v96
	v_lshlrev_b32_e32 v96, 16, v136
	v_pk_mul_f32 v[98:99], v[70:71], v[100:101] op_sel_hi:[1,0]
	s_nop 0
	v_pk_mul_f32 v[96:97], v[98:99], v[96:97]
	v_lshlrev_b32_e32 v98, 16, v137
	v_mfma_f32_32x32x16_bf16 v[16:31], v[108:111], v[132:135], v[16:31]
	v_and_b32_e32 v99, 0xffff0000, v137
	v_mul_f32_e64 v102, v68, v100
	v_mul_f32_e64 v103, v69, v100
	v_cvt_pk_bf16_f32 v96, v96, v97
	v_mul_f32_e64 v98, v102, v98
	v_mul_f32_e64 v99, v103, v99
	v_pk_mul_f32 v[102:103], v[66:67], v[100:101] op_sel_hi:[1,0]
	v_cvt_pk_bf16_f32 v97, v98, v99
	v_lshlrev_b32_e32 v98, 16, v138
	v_mfma_f32_32x32x16_bf16 v[0:15], v[112:115], v[132:135], v[0:15]
	v_and_b32_e32 v99, 0xffff0000, v138
	v_mul_f32_e64 v98, v102, v98
	v_mul_f32_e64 v99, v103, v99
	v_lshlrev_b32_e32 v102, 16, v139
	v_and_b32_e32 v103, 0xffff0000, v139
	v_pk_mul_f32 v[100:101], v[64:65], v[100:101] op_sel_hi:[1,0]
	v_cvt_pk_bf16_f32 v98, v98, v99
	v_pk_mul_f32 v[100:101], v[100:101], v[102:103]
	v_add_u32_e32 v102, 0xe400, v107
	v_cvt_pk_bf16_f32 v99, v100, v101
	v_add_u32_e32 v100, 0xd000, v78
	v_add_u32_e32 v101, 0xd800, v78
	v_mfma_f32_32x32x16_bf16 v[48:63], v[116:119], v[96:99], v[48:63]
	v_add_u32_e32 v103, 0xc400, v78
	v_mfma_f32_32x32x16_bf16 v[32:47], v[120:123], v[96:99], v[32:47]
	v_mfma_f32_32x32x16_bf16 v[16:31], v[124:127], v[96:99], v[16:31]
	v_mfma_f32_32x32x16_bf16 v[0:15], v[128:131], v[96:99], v[0:15]
	v_add_u32_e32 v98, 0x1400, v75
	v_add_u32_e32 v96, s77, v98
	v_ashrrev_i32_e32 v97, 31, v96
	v_lshl_add_u64 v[96:97], v[96:97], 1, s[6:7]
	global_load_lds_dwordx4 v[96:97], off nt
	v_add_u32_e32 v96, s78, v98
	v_ashrrev_i32_e32 v97, 31, v96
	v_lshl_add_u64 v[96:97], v[96:97], 1, s[8:9]
	s_mov_b32 m0, s49
	v_add_u32_e32 v99, 0xc800, v78
	global_load_lds_dwordx4 v[96:97], off nt
	v_add_u32_e32 v96, s79, v98
	v_ashrrev_i32_e32 v97, 31, v96
	v_lshl_add_u64 v[96:97], v[96:97], 1, s[40:41]
	s_mov_b32 m0, s48
	v_add_u32_e32 v98, 0xc000, v78
	global_load_lds_dwordx4 v[96:97], off nt
	v_add_u32_e32 v97, 0xe000, v107
	ds_read_b64_tr_b16 v[140:141], v97
	ds_read_b64_tr_b16 v[142:143], v97 offset:512
	ds_read_b64_tr_b16 v[108:109], v98
	ds_read_b64_tr_b16 v[110:111], v98 offset:512
	v_cvt_f32_i32_e32 v107, v105
	ds_read_b64_tr_b16 v[112:113], v99
	ds_read_b64_tr_b16 v[114:115], v99 offset:512
	ds_read_b64_tr_b16 v[116:117], v100
	ds_read_b64_tr_b16 v[118:119], v100 offset:512
	ds_read_b64_tr_b16 v[120:121], v101
	ds_read_b64_tr_b16 v[122:123], v101 offset:512
	ds_read_b64_tr_b16 v[144:145], v102
	ds_read_b64_tr_b16 v[146:147], v102 offset:512
	v_mul_f32_e32 v107, v174, v107
	ds_read_b64_tr_b16 v[124:125], v103
	ds_read_b64_tr_b16 v[126:127], v103 offset:512
	v_exp_f32_e32 v148, v107
	ds_read_b64_tr_b16 v[128:129], v104
	ds_read_b64_tr_b16 v[130:131], v104 offset:512
	v_add_u32_e32 v96, 0xd400, v78
	ds_read_b64_tr_b16 v[132:133], v96
	ds_read_b64_tr_b16 v[134:135], v96 offset:512
	v_add_u32_e32 v105, 0xdc00, v78
	ds_read_b64_tr_b16 v[136:137], v105
	ds_read_b64_tr_b16 v[138:139], v105 offset:512
	v_pk_mul_f32 v[152:153], v[70:71], v[148:149] op_sel_hi:[1,0]
	s_waitcnt lgkmcnt(0)
	v_sub_u32_e32 v107, 0xaf, v74
	v_lshlrev_b32_e32 v150, 16, v140
	v_and_b32_e32 v151, 0xffff0000, v140
	v_pk_mul_f32 v[150:151], v[152:153], v[150:151]
	v_pk_mul_f32 v[152:153], v[68:69], v[148:149] op_sel_hi:[1,0]
	v_cvt_pk_bf16_f32 v140, v150, v151
	v_lshlrev_b32_e32 v150, 16, v141
	v_and_b32_e32 v151, 0xffff0000, v141
	v_pk_mul_f32 v[150:151], v[152:153], v[150:151]
	v_pk_mul_f32 v[152:153], v[66:67], v[148:149] op_sel_hi:[1,0]
	v_cvt_pk_bf16_f32 v141, v150, v151
	v_lshlrev_b32_e32 v150, 16, v142
	v_and_b32_e32 v151, 0xffff0000, v142
	v_cvt_f32_i32_e32 v107, v107
	v_pk_mul_f32 v[150:151], v[152:153], v[150:151]
	v_pk_mul_f32 v[148:149], v[64:65], v[148:149] op_sel_hi:[1,0]
	v_cvt_pk_bf16_f32 v142, v150, v151
	v_lshlrev_b32_e32 v150, 16, v143
	v_and_b32_e32 v151, 0xffff0000, v143
	v_pk_mul_f32 v[148:149], v[148:149], v[150:151]
	v_mul_f32_e32 v107, v174, v107
	v_cvt_pk_bf16_f32 v143, v148, v149
	s_waitcnt vmcnt(6)
	s_barrier
	s_mov_b32 m0, s46
	v_mfma_f32_32x32x16_bf16 v[32:47], v[112:115], v[140:143], v[32:47]
	v_exp_f32_e32 v112, v107
	v_add_u32_e32 v107, 0x1800, v75
	v_add_u32_e32 v75, 0x1c00, v75
	v_pk_mul_f32 v[114:115], v[68:69], v[112:113] op_sel_hi:[1,0]
	v_mfma_f32_32x32x16_bf16 v[48:63], v[108:111], v[140:143], v[48:63]
	v_lshlrev_b32_e32 v108, 16, v144
	v_and_b32_e32 v109, 0xffff0000, v144
	v_mul_f32_e64 v110, v70, v112
	v_mul_f32_e64 v111, v71, v112
	v_mul_f32_e64 v108, v110, v108
	v_mul_f32_e64 v109, v111, v109
	v_lshlrev_b32_e32 v110, 16, v145
	v_and_b32_e32 v111, 0xffff0000, v145
	v_mfma_f32_32x32x16_bf16 v[16:31], v[116:119], v[140:143], v[16:31]
	v_mul_f32_e64 v110, v114, v110
	v_mul_f32_e64 v111, v115, v111
	v_cvt_pk_bf16_f32 v108, v108, v109
	v_cvt_pk_bf16_f32 v109, v110, v111
	v_lshlrev_b32_e32 v110, 16, v146
	v_and_b32_e32 v111, 0xffff0000, v146
	v_pk_mul_f32 v[114:115], v[66:67], v[112:113] op_sel_hi:[1,0]
	v_pk_mul_f32 v[112:113], v[64:65], v[112:113] op_sel_hi:[1,0]
	v_mfma_f32_32x32x16_bf16 v[0:15], v[120:123], v[140:143], v[0:15]
	v_mul_f32_e64 v110, v114, v110
	v_mul_f32_e64 v111, v115, v111
	v_lshlrev_b32_e32 v114, 16, v147
	v_and_b32_e32 v115, 0xffff0000, v147
	v_mul_f32_e64 v112, v112, v114
	v_mul_f32_e64 v113, v113, v115
	v_cvt_pk_bf16_f32 v110, v110, v111
	v_cvt_pk_bf16_f32 v111, v112, v113
	v_sub_u32_e32 v115, 0x9f, v74
	v_cvt_f32_i32_e32 v156, v115
	v_mfma_f32_32x32x16_bf16 v[48:63], v[124:127], v[108:111], v[48:63]
	v_mul_f32_e32 v156, v174, v156
	v_exp_f32_e32 v156, v156
	s_nop 0
	v_pk_mul_f32 v[160:161], v[70:71], v[156:157] op_sel_hi:[1,0]
	v_mfma_f32_32x32x16_bf16 v[32:47], v[128:131], v[108:111], v[32:47]
	v_mfma_f32_32x32x16_bf16 v[16:31], v[132:135], v[108:111], v[16:31]
	v_mfma_f32_32x32x16_bf16 v[0:15], v[136:139], v[108:111], v[0:15]
	v_add_u32_e32 v108, s77, v107
	v_ashrrev_i32_e32 v109, 31, v108
	v_lshl_add_u64 v[108:109], v[108:109], 1, s[6:7]
	global_load_lds_dwordx4 v[108:109], off nt
	v_add_u32_e32 v108, s78, v107
	v_ashrrev_i32_e32 v109, 31, v108
	v_lshl_add_u64 v[108:109], v[108:109], 1, s[8:9]
	s_mov_b32 m0, s45
	s_nop 0
	global_load_lds_dwordx4 v[108:109], off nt
	v_add_u32_e32 v108, s79, v107
	v_ashrrev_i32_e32 v109, 31, v108
	v_lshl_add_u64 v[108:109], v[108:109], 1, s[40:41]
	s_mov_b32 m0, s44
	v_add_u32_e32 v107, s47, v106
	global_load_lds_dwordx4 v[108:109], off nt
	ds_read_b64_tr_b16 v[148:149], v107
	ds_read_b64_tr_b16 v[150:151], v107 offset:512
	v_add_u32_e32 v108, s72, v106
	ds_read_b64_tr_b16 v[116:117], v108
	ds_read_b64_tr_b16 v[118:119], v108 offset:512
	v_add_u32_e32 v109, 0x800, v108
	ds_read_b64_tr_b16 v[120:121], v109
	ds_read_b64_tr_b16 v[122:123], v109 offset:512
	v_add_u32_e32 v110, 0x1000, v108
	ds_read_b64_tr_b16 v[124:125], v110
	ds_read_b64_tr_b16 v[126:127], v110 offset:512
	v_add_u32_e32 v111, 0x1800, v108
	ds_read_b64_tr_b16 v[128:129], v111
	ds_read_b64_tr_b16 v[130:131], v111 offset:512
	v_add_u32_e32 v112, 0x400, v107
	ds_read_b64_tr_b16 v[152:153], v112
	ds_read_b64_tr_b16 v[154:155], v112 offset:512
	v_add_u32_e32 v113, 0x400, v108
	ds_read_b64_tr_b16 v[132:133], v113
	ds_read_b64_tr_b16 v[134:135], v113 offset:512
	v_add_u32_e32 v114, 0xc00, v108
	ds_read_b64_tr_b16 v[136:137], v114
	ds_read_b64_tr_b16 v[138:139], v114 offset:512
	v_add_u32_e32 v106, 0x1400, v108
	ds_read_b64_tr_b16 v[140:141], v106
	ds_read_b64_tr_b16 v[142:143], v106 offset:512
	v_add_u32_e32 v115, 0x1c00, v108
	ds_read_b64_tr_b16 v[144:145], v115
	ds_read_b64_tr_b16 v[146:147], v115 offset:512
	s_mov_b32 m0, s43
	s_waitcnt lgkmcnt(0)
	s_waitcnt vmcnt(6)
	s_barrier
	v_lshlrev_b32_e32 v158, 16, v148
	v_and_b32_e32 v159, 0xffff0000, v148
	v_pk_mul_f32 v[158:159], v[160:161], v[158:159]
	v_pk_mul_f32 v[160:161], v[68:69], v[156:157] op_sel_hi:[1,0]
	v_cvt_pk_bf16_f32 v148, v158, v159
	v_lshlrev_b32_e32 v158, 16, v149
	v_and_b32_e32 v159, 0xffff0000, v149
	v_pk_mul_f32 v[158:159], v[160:161], v[158:159]
	v_pk_mul_f32 v[160:161], v[66:67], v[156:157] op_sel_hi:[1,0]
	v_cvt_pk_bf16_f32 v149, v158, v159
	v_lshlrev_b32_e32 v158, 16, v150
	v_and_b32_e32 v159, 0xffff0000, v150
	v_pk_mul_f32 v[158:159], v[160:161], v[158:159]
	v_pk_mul_f32 v[156:157], v[64:65], v[156:157] op_sel_hi:[1,0]
	v_cvt_pk_bf16_f32 v150, v158, v159
	v_lshlrev_b32_e32 v158, 16, v151
	v_and_b32_e32 v159, 0xffff0000, v151
	v_pk_mul_f32 v[156:157], v[156:157], v[158:159]
	s_nop 0
	v_cvt_pk_bf16_f32 v151, v156, v157
	s_nop 1
	v_mfma_f32_32x32x16_bf16 v[48:63], v[116:119], v[148:151], v[48:63]
	v_sub_u32_e32 v116, 0x8f, v74
	v_cvt_f32_i32_e32 v116, v116
	v_and_b32_e32 v117, 0xffff0000, v152
	v_mul_f32_e32 v116, v174, v116
	v_mfma_f32_32x32x16_bf16 v[32:47], v[120:123], v[148:151], v[32:47]
	v_exp_f32_e32 v120, v116
	v_lshlrev_b32_e32 v116, 16, v152
	v_pk_mul_f32 v[118:119], v[70:71], v[120:121] op_sel_hi:[1,0]
	s_nop 0
	v_pk_mul_f32 v[116:117], v[118:119], v[116:117]
	v_lshlrev_b32_e32 v118, 16, v153
	v_mfma_f32_32x32x16_bf16 v[16:31], v[124:127], v[148:151], v[16:31]
	v_and_b32_e32 v119, 0xffff0000, v153
	v_mul_f32_e64 v122, v68, v120
	v_mul_f32_e64 v123, v69, v120
	v_cvt_pk_bf16_f32 v116, v116, v117
	v_mul_f32_e64 v118, v122, v118
	v_mul_f32_e64 v119, v123, v119
	v_pk_mul_f32 v[122:123], v[66:67], v[120:121] op_sel_hi:[1,0]
	v_cvt_pk_bf16_f32 v117, v118, v119
	v_lshlrev_b32_e32 v118, 16, v154
	v_mfma_f32_32x32x16_bf16 v[0:15], v[128:131], v[148:151], v[0:15]
	v_and_b32_e32 v119, 0xffff0000, v154
	v_mul_f32_e64 v118, v122, v118
	v_mul_f32_e64 v119, v123, v119
	v_lshlrev_b32_e32 v122, 16, v155
	v_and_b32_e32 v123, 0xffff0000, v155
	v_pk_mul_f32 v[120:121], v[64:65], v[120:121] op_sel_hi:[1,0]
	v_cvt_pk_bf16_f32 v118, v118, v119
	v_pk_mul_f32 v[120:121], v[120:121], v[122:123]
	s_nop 0
	v_cvt_pk_bf16_f32 v119, v120, v121
	s_nop 1
	v_mfma_f32_32x32x16_bf16 v[48:63], v[132:135], v[116:119], v[48:63]
	v_mfma_f32_32x32x16_bf16 v[32:47], v[136:139], v[116:119], v[32:47]
	v_mfma_f32_32x32x16_bf16 v[16:31], v[140:143], v[116:119], v[16:31]
	v_mfma_f32_32x32x16_bf16 v[0:15], v[144:147], v[116:119], v[0:15]
	v_add_u32_e32 v116, s77, v75
	v_ashrrev_i32_e32 v117, 31, v116
	v_lshl_add_u64 v[116:117], v[116:117], 1, s[6:7]
	global_load_lds_dwordx4 v[116:117], off nt
	v_add_u32_e32 v116, s78, v75
	v_ashrrev_i32_e32 v117, 31, v116
	v_lshl_add_u64 v[116:117], v[116:117], 1, s[8:9]
	s_mov_b32 m0, s42
	s_add_u32 s8, s54, 0xec00000
	global_load_lds_dwordx4 v[116:117], off nt
	v_add_u32_e32 v116, s79, v75
	v_ashrrev_i32_e32 v117, 31, v116
	v_lshl_add_u64 v[116:117], v[116:117], 1, s[40:41]
	s_mov_b32 m0, s5
	v_sub_u32_e32 v75, 0x7f, v74
	global_load_lds_dwordx4 v[116:117], off nt
	ds_read_b64_tr_b16 v[144:145], v77
	ds_read_b64_tr_b16 v[146:147], v77 offset:512
	ds_read_b64_tr_b16 v[116:117], v78
	ds_read_b64_tr_b16 v[118:119], v78 offset:512
	ds_read_b64_tr_b16 v[120:121], v79
	ds_read_b64_tr_b16 v[122:123], v79 offset:512
	ds_read_b64_tr_b16 v[124:125], v80
	ds_read_b64_tr_b16 v[126:127], v80 offset:512
	v_cvt_f32_i32_e32 v75, v75
	ds_read_b64_tr_b16 v[128:129], v81
	ds_read_b64_tr_b16 v[130:131], v81 offset:512
	ds_read_b64_tr_b16 v[148:149], v82
	ds_read_b64_tr_b16 v[150:151], v82 offset:512
	ds_read_b64_tr_b16 v[78:79], v83
	ds_read_b64_tr_b16 v[80:81], v83 offset:512
	ds_read_b64_tr_b16 v[132:133], v84
	ds_read_b64_tr_b16 v[134:135], v84 offset:512
	v_mul_f32_e32 v75, v174, v75
	ds_read_b64_tr_b16 v[136:137], v76
	ds_read_b64_tr_b16 v[138:139], v76 offset:512
	v_exp_f32_e32 v76, v75
	ds_read_b64_tr_b16 v[140:141], v85
	ds_read_b64_tr_b16 v[142:143], v85 offset:512
	v_sub_u32_e32 v75, 0x6f, v74
	s_waitcnt lgkmcnt(0)
	v_pk_mul_f32 v[84:85], v[70:71], v[76:77] op_sel_hi:[1,0]
	v_lshlrev_b32_e32 v82, 16, v144
	v_and_b32_e32 v83, 0xffff0000, v144
	v_pk_mul_f32 v[82:83], v[84:85], v[82:83]
	v_lshlrev_b32_e32 v84, 16, v145
	v_and_b32_e32 v85, 0xffff0000, v145
	v_pk_mul_f32 v[144:145], v[68:69], v[76:77] op_sel_hi:[1,0]
	v_cvt_f32_i32_e32 v75, v75
	v_pk_mul_f32 v[84:85], v[144:145], v[84:85]
	v_cvt_pk_bf16_f32 v82, v82, v83
	v_cvt_pk_bf16_f32 v83, v84, v85
	v_lshlrev_b32_e32 v84, 16, v146
	v_and_b32_e32 v85, 0xffff0000, v146
	v_pk_mul_f32 v[144:145], v[66:67], v[76:77] op_sel_hi:[1,0]
	v_pk_mul_f32 v[76:77], v[64:65], v[76:77] op_sel_hi:[1,0]
	v_pk_mul_f32 v[84:85], v[144:145], v[84:85]
	v_lshlrev_b32_e32 v144, 16, v147
	v_and_b32_e32 v145, 0xffff0000, v147
	v_pk_mul_f32 v[76:77], v[76:77], v[144:145]
	v_mul_f32_e32 v75, v174, v75
	v_cvt_pk_bf16_f32 v84, v84, v85
	v_cvt_pk_bf16_f32 v85, v76, v77
	v_exp_f32_e32 v76, v75
	s_waitcnt vmcnt(6)
	s_barrier
	v_mfma_f32_32x32x16_bf16 v[32:47], v[120:123], v[82:85], v[32:47]
	v_sub_u32_e32 v75, 0x5f, v74
	v_cvt_f32_i32_e32 v75, v75
	s_addc_u32 s9, s55, 0
	s_ashr_i32 s5, s4, 31
	s_lshl_b64 s[4:5], s[4:5], 16
	v_mul_f32_e32 v75, v174, v75
	v_mfma_f32_32x32x16_bf16 v[48:63], v[116:119], v[82:85], v[48:63]
	v_mul_f32_e64 v116, v68, v76
	v_mul_f32_e64 v117, v69, v76
	s_add_u32 s40, s8, s4
	s_addc_u32 s41, s9, s5
	s_lshl_b32 s86, s62, 5
	s_movk_i32 s42, 0x110
	s_and_b32 s5, s41, 0xffff
	s_mov_b32 s7, 0x20000
	v_mfma_f32_32x32x16_bf16 v[16:31], v[124:127], v[82:85], v[16:31]
	s_mov_b32 s6, 0x10000
	s_mov_b32 s4, s40
	s_lshl_b32 s87, s81, 6
	v_mfma_f32_32x32x16_bf16 v[0:15], v[128:131], v[82:85], v[0:15]
	v_lshlrev_b32_e32 v82, 16, v148
	v_and_b32_e32 v83, 0xffff0000, v148
	v_mul_f32_e64 v84, v70, v76
	v_mul_f32_e64 v85, v71, v76
	v_mul_f32_e64 v82, v84, v82
	v_mul_f32_e64 v83, v85, v83
	v_lshlrev_b32_e32 v84, 16, v149
	v_and_b32_e32 v85, 0xffff0000, v149
	v_pk_mul_f32 v[84:85], v[116:117], v[84:85]
	v_cvt_pk_bf16_f32 v82, v82, v83
	v_cvt_pk_bf16_f32 v83, v84, v85
	v_lshlrev_b32_e32 v84, 16, v150
	v_and_b32_e32 v85, 0xffff0000, v150
	v_pk_mul_f32 v[116:117], v[66:67], v[76:77] op_sel_hi:[1,0]
	v_pk_mul_f32 v[76:77], v[64:65], v[76:77] op_sel_hi:[1,0]
	v_pk_mul_f32 v[84:85], v[116:117], v[84:85]
	v_lshlrev_b32_e32 v116, 16, v151
	v_and_b32_e32 v117, 0xffff0000, v151
	v_pk_mul_f32 v[76:77], v[76:77], v[116:117]
	v_cvt_pk_bf16_f32 v84, v84, v85
	v_cvt_pk_bf16_f32 v85, v76, v77
	s_nop 1
	v_mfma_f32_32x32x16_bf16 v[32:47], v[132:135], v[82:85], v[32:47]
	ds_read_b64_tr_b16 v[132:133], v87
	ds_read_b64_tr_b16 v[134:135], v87 offset:512
	v_mfma_f32_32x32x16_bf16 v[48:63], v[78:81], v[82:85], v[48:63]
	ds_read_b64_tr_b16 v[76:77], v88
	ds_read_b64_tr_b16 v[78:79], v88 offset:512
	v_mfma_f32_32x32x16_bf16 v[16:31], v[136:139], v[82:85], v[16:31]
	v_mfma_f32_32x32x16_bf16 v[0:15], v[140:143], v[82:85], v[0:15]
	ds_read_b64_tr_b16 v[80:81], v89
	ds_read_b64_tr_b16 v[82:83], v89 offset:512
	ds_read_b64_tr_b16 v[116:117], v90
	ds_read_b64_tr_b16 v[118:119], v90 offset:512
	ds_read_b64_tr_b16 v[120:121], v91
	ds_read_b64_tr_b16 v[122:123], v91 offset:512
	ds_read_b64_tr_b16 v[136:137], v92
	ds_read_b64_tr_b16 v[138:139], v92 offset:512
	ds_read_b64_tr_b16 v[88:89], v93
	ds_read_b64_tr_b16 v[90:91], v93 offset:512
	v_exp_f32_e32 v140, v75
	ds_read_b64_tr_b16 v[124:125], v94
	ds_read_b64_tr_b16 v[126:127], v94 offset:512
	ds_read_b64_tr_b16 v[128:129], v86
	ds_read_b64_tr_b16 v[130:131], v86 offset:512
	ds_read_b64_tr_b16 v[84:85], v95
	ds_read_b64_tr_b16 v[86:87], v95 offset:512
	v_sub_u32_e32 v75, 0x4f, v74
	s_waitcnt lgkmcnt(0)
	v_pk_mul_f32 v[94:95], v[70:71], v[140:141] op_sel_hi:[1,0]
	v_lshlrev_b32_e32 v92, 16, v132
	v_and_b32_e32 v93, 0xffff0000, v132
	v_pk_mul_f32 v[92:93], v[94:95], v[92:93]
	v_lshlrev_b32_e32 v94, 16, v133
	v_and_b32_e32 v95, 0xffff0000, v133
	v_pk_mul_f32 v[132:133], v[68:69], v[140:141] op_sel_hi:[1,0]
	v_cvt_f32_i32_e32 v75, v75
	v_pk_mul_f32 v[94:95], v[132:133], v[94:95]
	v_cvt_pk_bf16_f32 v92, v92, v93
	v_cvt_pk_bf16_f32 v93, v94, v95
	v_lshlrev_b32_e32 v94, 16, v134
	v_and_b32_e32 v95, 0xffff0000, v134
	v_pk_mul_f32 v[132:133], v[66:67], v[140:141] op_sel_hi:[1,0]
	v_mul_f32_e32 v75, v174, v75
	v_pk_mul_f32 v[94:95], v[132:133], v[94:95]
	v_lshlrev_b32_e32 v132, 16, v135
	v_and_b32_e32 v133, 0xffff0000, v135
	v_pk_mul_f32 v[134:135], v[64:65], v[140:141] op_sel_hi:[1,0]
	v_cvt_pk_bf16_f32 v94, v94, v95
	v_pk_mul_f32 v[132:133], v[134:135], v[132:133]
	s_waitcnt vmcnt(3)
	s_barrier
	v_cvt_pk_bf16_f32 v95, v132, v133
	s_nop 1
	v_mfma_f32_32x32x16_bf16 v[32:47], v[80:83], v[92:95], v[32:47]
	v_exp_f32_e32 v80, v75
	v_sub_u32_e32 v75, 63, v74
	v_cvt_f32_i32_e32 v75, v75
	v_pk_mul_f32 v[82:83], v[68:69], v[80:81] op_sel_hi:[1,0]
	v_mul_f32_e32 v75, v174, v75
	v_mfma_f32_32x32x16_bf16 v[48:63], v[76:79], v[92:95], v[48:63]
	v_lshlrev_b32_e32 v76, 16, v136
	v_and_b32_e32 v77, 0xffff0000, v136
	v_mul_f32_e64 v78, v70, v80
	v_mul_f32_e64 v79, v71, v80
	v_mul_f32_e64 v76, v78, v76
	v_mul_f32_e64 v77, v79, v77
	v_lshlrev_b32_e32 v78, 16, v137
	v_and_b32_e32 v79, 0xffff0000, v137
	v_mfma_f32_32x32x16_bf16 v[16:31], v[116:119], v[92:95], v[16:31]
	v_mul_f32_e64 v78, v82, v78
	v_mul_f32_e64 v79, v83, v79
	v_cvt_pk_bf16_f32 v76, v76, v77
	v_cvt_pk_bf16_f32 v77, v78, v79
	v_lshlrev_b32_e32 v78, 16, v138
	v_and_b32_e32 v79, 0xffff0000, v138
	v_pk_mul_f32 v[82:83], v[66:67], v[80:81] op_sel_hi:[1,0]
	v_pk_mul_f32 v[80:81], v[64:65], v[80:81] op_sel_hi:[1,0]
	v_mfma_f32_32x32x16_bf16 v[0:15], v[120:123], v[92:95], v[0:15]
	v_mul_f32_e64 v78, v82, v78
	v_mul_f32_e64 v79, v83, v79
	v_lshlrev_b32_e32 v82, 16, v139
	v_and_b32_e32 v83, 0xffff0000, v139
	v_mul_f32_e64 v80, v80, v82
	v_mul_f32_e64 v81, v81, v83
	v_cvt_pk_bf16_f32 v78, v78, v79
	v_cvt_pk_bf16_f32 v79, v80, v81
	s_nop 1
	v_mfma_f32_32x32x16_bf16 v[32:47], v[124:127], v[76:79], v[32:47]
	ds_read_b64_tr_b16 v[124:125], v97
	ds_read_b64_tr_b16 v[126:127], v97 offset:512
	v_mfma_f32_32x32x16_bf16 v[48:63], v[88:91], v[76:79], v[48:63]
	v_mfma_f32_32x32x16_bf16 v[16:31], v[128:131], v[76:79], v[16:31]
	v_mfma_f32_32x32x16_bf16 v[0:15], v[84:87], v[76:79], v[0:15]
	ds_read_b64_tr_b16 v[76:77], v98
	ds_read_b64_tr_b16 v[78:79], v98 offset:512
	ds_read_b64_tr_b16 v[80:81], v99
	ds_read_b64_tr_b16 v[82:83], v99 offset:512
	ds_read_b64_tr_b16 v[84:85], v100
	ds_read_b64_tr_b16 v[86:87], v100 offset:512
	ds_read_b64_tr_b16 v[88:89], v101
	ds_read_b64_tr_b16 v[90:91], v101 offset:512
	ds_read_b64_tr_b16 v[128:129], v102
	ds_read_b64_tr_b16 v[130:131], v102 offset:512
	ds_read_b64_tr_b16 v[92:93], v103
	ds_read_b64_tr_b16 v[94:95], v103 offset:512
	ds_read_b64_tr_b16 v[98:99], v104
	ds_read_b64_tr_b16 v[100:101], v104 offset:512
	ds_read_b64_tr_b16 v[116:117], v96
	ds_read_b64_tr_b16 v[118:119], v96 offset:512
	v_exp_f32_e32 v96, v75
	ds_read_b64_tr_b16 v[120:121], v105
	ds_read_b64_tr_b16 v[122:123], v105 offset:512
	v_sub_u32_e32 v75, 47, v74
	s_waitcnt lgkmcnt(0)
	v_pk_mul_f32 v[104:105], v[70:71], v[96:97] op_sel_hi:[1,0]
	v_lshlrev_b32_e32 v102, 16, v124
	v_and_b32_e32 v103, 0xffff0000, v124
	v_pk_mul_f32 v[102:103], v[104:105], v[102:103]
	v_lshlrev_b32_e32 v104, 16, v125
	v_and_b32_e32 v105, 0xffff0000, v125
	v_pk_mul_f32 v[124:125], v[68:69], v[96:97] op_sel_hi:[1,0]
	v_cvt_f32_i32_e32 v75, v75
	v_pk_mul_f32 v[104:105], v[124:125], v[104:105]
	v_cvt_pk_bf16_f32 v102, v102, v103
	v_cvt_pk_bf16_f32 v103, v104, v105
	v_lshlrev_b32_e32 v104, 16, v126
	v_and_b32_e32 v105, 0xffff0000, v126
	v_pk_mul_f32 v[124:125], v[66:67], v[96:97] op_sel_hi:[1,0]
	v_pk_mul_f32 v[96:97], v[64:65], v[96:97] op_sel_hi:[1,0]
	v_pk_mul_f32 v[104:105], v[124:125], v[104:105]
	v_lshlrev_b32_e32 v124, 16, v127
	v_and_b32_e32 v125, 0xffff0000, v127
	v_pk_mul_f32 v[96:97], v[96:97], v[124:125]
	v_cvt_pk_bf16_f32 v104, v104, v105
	v_cvt_pk_bf16_f32 v105, v96, v97
	v_mul_f32_e32 v75, v174, v75
	s_waitcnt vmcnt(0)
	s_barrier
	v_mfma_f32_32x32x16_bf16 v[32:47], v[80:83], v[102:105], v[32:47]
	v_exp_f32_e32 v80, v75
	v_sub_u32_e32 v75, 31, v74
	v_cvt_f32_i32_e32 v75, v75
	v_pk_mul_f32 v[82:83], v[68:69], v[80:81] op_sel_hi:[1,0]
	v_sub_u32_e32 v74, 15, v74
	v_cvt_f32_i32_e32 v74, v74
	v_mfma_f32_32x32x16_bf16 v[16:31], v[84:87], v[102:105], v[16:31]
	v_mul_f32_e32 v75, v174, v75
	v_mul_f32_e32 v74, v174, v74
	v_mfma_f32_32x32x16_bf16 v[48:63], v[76:79], v[102:105], v[48:63]
	v_lshlrev_b32_e32 v76, 16, v128
	v_and_b32_e32 v77, 0xffff0000, v128
	v_mul_f32_e64 v78, v70, v80
	v_mul_f32_e64 v79, v71, v80
	v_mul_f32_e64 v76, v78, v76
	v_mul_f32_e64 v77, v79, v77
	v_lshlrev_b32_e32 v78, 16, v129
	v_and_b32_e32 v79, 0xffff0000, v129
	v_mfma_f32_32x32x16_bf16 v[0:15], v[88:91], v[102:105], v[0:15]
	v_mul_f32_e64 v78, v82, v78
	v_mul_f32_e64 v79, v83, v79
	v_cvt_pk_bf16_f32 v76, v76, v77
	v_cvt_pk_bf16_f32 v77, v78, v79
	v_lshlrev_b32_e32 v78, 16, v130
	v_and_b32_e32 v79, 0xffff0000, v130
	v_pk_mul_f32 v[82:83], v[66:67], v[80:81] op_sel_hi:[1,0]
	v_pk_mul_f32 v[80:81], v[64:65], v[80:81] op_sel_hi:[1,0]
	v_pk_mul_f32 v[78:79], v[82:83], v[78:79]
	v_lshlrev_b32_e32 v82, 16, v131
	v_and_b32_e32 v83, 0xffff0000, v131
	v_pk_mul_f32 v[80:81], v[80:81], v[82:83]
	v_cvt_pk_bf16_f32 v78, v78, v79
	v_cvt_pk_bf16_f32 v79, v80, v81
	s_nop 1
	v_mfma_f32_32x32x16_bf16 v[16:31], v[116:119], v[76:79], v[16:31]
	ds_read_b64_tr_b16 v[116:117], v107
	ds_read_b64_tr_b16 v[118:119], v107 offset:512
	v_mfma_f32_32x32x16_bf16 v[48:63], v[92:95], v[76:79], v[48:63]
	v_mfma_f32_32x32x16_bf16 v[32:47], v[98:101], v[76:79], v[32:47]
	v_mfma_f32_32x32x16_bf16 v[0:15], v[120:123], v[76:79], v[0:15]
	ds_read_b64_tr_b16 v[76:77], v108
	ds_read_b64_tr_b16 v[78:79], v108 offset:512
	ds_read_b64_tr_b16 v[80:81], v109
	ds_read_b64_tr_b16 v[82:83], v109 offset:512
	ds_read_b64_tr_b16 v[84:85], v110
	ds_read_b64_tr_b16 v[86:87], v110 offset:512
	ds_read_b64_tr_b16 v[88:89], v111
	ds_read_b64_tr_b16 v[90:91], v111 offset:512
	ds_read_b64_tr_b16 v[120:121], v112
	ds_read_b64_tr_b16 v[122:123], v112 offset:512
	ds_read_b64_tr_b16 v[92:93], v113
	ds_read_b64_tr_b16 v[94:95], v113 offset:512
	v_exp_f32_e32 v112, v75
	ds_read_b64_tr_b16 v[96:97], v114
	ds_read_b64_tr_b16 v[98:99], v114 offset:512
	ds_read_b64_tr_b16 v[100:101], v106
	ds_read_b64_tr_b16 v[102:103], v106 offset:512
	ds_read_b64_tr_b16 v[104:105], v115
	ds_read_b64_tr_b16 v[106:107], v115 offset:512
	s_nop 0
	s_waitcnt lgkmcnt(0)
	v_pk_mul_f32 v[110:111], v[70:71], v[112:113] op_sel_hi:[1,0]
	v_lshlrev_b32_e32 v108, 16, v116
	v_and_b32_e32 v109, 0xffff0000, v116
	v_pk_mul_f32 v[108:109], v[110:111], v[108:109]
	v_lshlrev_b32_e32 v110, 16, v117
	v_and_b32_e32 v111, 0xffff0000, v117
	v_pk_mul_f32 v[114:115], v[68:69], v[112:113] op_sel_hi:[1,0]
	v_cvt_pk_bf16_f32 v108, v108, v109
	v_pk_mul_f32 v[110:111], v[114:115], v[110:111]
	v_pk_mul_f32 v[114:115], v[66:67], v[112:113] op_sel_hi:[1,0]
	v_cvt_pk_bf16_f32 v109, v110, v111
	v_lshlrev_b32_e32 v110, 16, v118
	v_and_b32_e32 v111, 0xffff0000, v118
	v_pk_mul_f32 v[110:111], v[114:115], v[110:111]
	v_lshlrev_b32_e32 v114, 16, v119
	v_and_b32_e32 v115, 0xffff0000, v119
	v_pk_mul_f32 v[112:113], v[64:65], v[112:113] op_sel_hi:[1,0]
	v_cvt_pk_bf16_f32 v110, v110, v111
	v_pk_mul_f32 v[112:113], v[112:113], v[114:115]
	v_and_b32_e32 v75, 0xffff0000, v120
	v_cvt_pk_bf16_f32 v111, v112, v113
	s_nop 1
	v_mfma_f32_32x32x16_bf16 v[48:63], v[76:79], v[108:111], v[48:63]
	v_exp_f32_e32 v78, v74
	v_lshlrev_b32_e32 v74, 16, v120
	v_pk_mul_f32 v[70:71], v[70:71], v[78:79] op_sel_hi:[1,0]
	s_nop 0
	v_pk_mul_f32 v[70:71], v[70:71], v[74:75]
	v_pk_mul_f32 v[68:69], v[68:69], v[78:79] op_sel_hi:[1,0]
	v_mfma_f32_32x32x16_bf16 v[0:15], v[88:91], v[108:111], v[0:15]
	v_cvt_pk_bf16_f32 v74, v70, v71
	v_lshlrev_b32_e32 v70, 16, v121
	v_and_b32_e32 v71, 0xffff0000, v121
	v_mul_f32_e64 v68, v68, v70
	v_mul_f32_e64 v69, v69, v71
	v_pk_mul_f32 v[66:67], v[66:67], v[78:79] op_sel_hi:[1,0]
	v_cvt_pk_bf16_f32 v75, v68, v69
	v_lshlrev_b32_e32 v68, 16, v122
	v_and_b32_e32 v69, 0xffff0000, v122
	v_mfma_f32_32x32x16_bf16 v[32:47], v[80:83], v[108:111], v[32:47]
	v_mul_f32_e64 v66, v66, v68
	v_mul_f32_e64 v67, v67, v69
	v_mul_f32_e64 v64, v64, v78
	v_mul_f32_e64 v65, v65, v78
	v_cvt_pk_bf16_f32 v76, v66, v67
	v_lshlrev_b32_e32 v66, 16, v123
	v_and_b32_e32 v67, 0xffff0000, v123
	v_pk_mul_f32 v[64:65], v[64:65], v[66:67]
	v_mfma_f32_32x32x16_bf16 v[16:31], v[84:87], v[108:111], v[16:31]
	v_cvt_pk_bf16_f32 v77, v64, v65
	v_and_or_b32 v64, v72, 31, s86
	v_mul_lo_u32 v64, v64, s42
	v_lshlrev_b32_e32 v65, 4, v73
	v_mfma_f32_32x32x16_bf16 v[0:15], v[104:107], v[74:77], v[0:15]
	v_mfma_f32_32x32x16_bf16 v[48:63], v[92:95], v[74:77], v[48:63]
	s_nop 10
	v_cvt_pk_bf16_f32 v0, v0, v1
	v_cvt_pk_bf16_f32 v1, v2, v3
	v_cvt_pk_bf16_f32 v2, v4, v5
	v_cvt_pk_bf16_f32 v3, v6, v7
	s_nop 0
	v_permlane32_swap_b32_e32 v0, v2
	v_permlane32_swap_b32_e32 v1, v3
	v_mfma_f32_32x32x16_bf16 v[32:47], v[96:99], v[74:77], v[32:47]
	v_cvt_pk_bf16_f32 v48, v48, v49
	v_cvt_pk_bf16_f32 v49, v50, v51
	v_cvt_pk_bf16_f32 v50, v52, v53
	v_add3_u32 v52, 0, v64, v65
	ds_write_b128 v52, v[0:3] offset:192
	v_cvt_pk_bf16_f32 v0, v8, v9
	v_cvt_pk_bf16_f32 v1, v10, v11
	v_mfma_f32_32x32x16_bf16 v[16:31], v[100:103], v[74:77], v[16:31]
	v_cvt_pk_bf16_f32 v2, v12, v13
	v_cvt_pk_bf16_f32 v3, v14, v15
	s_nop 0
	v_permlane32_swap_b32_e32 v0, v2
	v_permlane32_swap_b32_e32 v1, v3
	v_cvt_pk_bf16_f32 v51, v54, v55
	v_cvt_pk_bf16_f32 v32, v32, v33
	v_cvt_pk_bf16_f32 v33, v34, v35
	v_cvt_pk_bf16_f32 v34, v36, v37
	v_cvt_pk_bf16_f32 v35, v38, v39
	s_nop 1
	v_cvt_pk_bf16_f32 v16, v16, v17
	v_cvt_pk_bf16_f32 v17, v18, v19
	v_cvt_pk_bf16_f32 v18, v20, v21
	v_cvt_pk_bf16_f32 v19, v22, v23
	ds_write_b128 v52, v[0:3] offset:224
	v_add_u32_e32 v12, s97, v72
	v_lshlrev_b32_e32 v0, 4, v72
	v_permlane32_swap_b32_e32 v48, v50
	v_permlane32_swap_b32_e32 v49, v51
	v_permlane32_swap_b32_e32 v32, v34
	v_permlane32_swap_b32_e32 v33, v35
	v_permlane32_swap_b32_e32 v16, v18
	v_permlane32_swap_b32_e32 v17, v19
	v_and_b32_e32 v13, 0xf0, v0
	v_lshrrev_b32_e32 v0, 4, v12
	ds_write_b128 v52, v[48:51]
	v_cvt_pk_bf16_f32 v48, v56, v57
	v_cvt_pk_bf16_f32 v49, v58, v59
	v_cvt_pk_bf16_f32 v50, v60, v61
	v_cvt_pk_bf16_f32 v51, v62, v63
	ds_write_b128 v52, v[32:35] offset:64
	v_cvt_pk_bf16_f32 v32, v40, v41
	v_cvt_pk_bf16_f32 v33, v42, v43
	v_cvt_pk_bf16_f32 v34, v44, v45
	v_cvt_pk_bf16_f32 v35, v46, v47
	ds_write_b128 v52, v[16:19] offset:128
	v_cvt_pk_bf16_f32 v16, v24, v25
	v_cvt_pk_bf16_f32 v17, v26, v27
	v_cvt_pk_bf16_f32 v18, v28, v29
	v_cvt_pk_bf16_f32 v19, v30, v31
	v_mul_lo_u32 v0, v0, s42
	v_permlane32_swap_b32_e32 v48, v50
	v_permlane32_swap_b32_e32 v49, v51
	v_permlane32_swap_b32_e32 v32, v34
	v_permlane32_swap_b32_e32 v33, v35
	v_permlane32_swap_b32_e32 v16, v18
	v_permlane32_swap_b32_e32 v17, v19
	v_add3_u32 v0, 0, v0, v13
	ds_write_b128 v52, v[48:51] offset:32
	ds_write_b128 v52, v[32:35] offset:96
	ds_write_b128 v52, v[16:19] offset:160
	s_waitcnt vmcnt(0) lgkmcnt(0)
	s_barrier
	ds_read_b128 v[0:3], v0
	v_add_u32_e32 v9, 0x200, v12
	v_lshrrev_b32_e32 v4, 4, v9
	v_mul_lo_u32 v4, v4, s42
	v_lshlrev_b32_e32 v8, 4, v12
	v_add3_u32 v4, 0, v4, v13
	v_add_u32_e32 v15, 0x400, v12
	ds_read_b128 v[4:7], v4
	s_waitcnt lgkmcnt(1)
	buffer_store_dwordx4 v[0:3], v8, s[4:7], 0 offen sc1
	v_add_u32_e32 v16, 0x600, v12
	v_lshrrev_b32_e32 v8, 4, v16
	v_lshrrev_b32_e32 v0, 4, v15
	v_mul_lo_u32 v0, v0, s42
	v_add3_u32 v0, 0, v0, v13
	v_mul_lo_u32 v8, v8, s42
	ds_read_b128 v[0:3], v0
	v_add3_u32 v8, 0, v8, v13
	v_lshlrev_b32_e32 v14, 4, v9
	ds_read_b128 v[8:11], v8
	s_waitcnt lgkmcnt(2)
	buffer_store_dwordx4 v[4:7], v14, s[4:7], 0 offen sc1
	s_nop 1
	v_lshlrev_b32_e32 v4, 4, v15
	s_waitcnt lgkmcnt(1)
	buffer_store_dwordx4 v[0:3], v4, s[4:7], 0 offen sc1
	v_add_u32_e32 v15, 0xc00, v12
	s_nop 0
	v_lshlrev_b32_e32 v0, 4, v16
	s_waitcnt lgkmcnt(0)
	buffer_store_dwordx4 v[8:11], v0, s[4:7], 0 offen sc1
	v_add_u32_e32 v0, 0x800, v12
	s_nop 0
	v_lshlrev_b32_e32 v8, 4, v0
	v_lshrrev_b32_e32 v0, 4, v0
	v_mul_lo_u32 v0, v0, s42
	v_add3_u32 v0, 0, v0, v13
	ds_read_b128 v[0:3], v0
	v_add_u32_e32 v9, 0xa00, v12
	v_lshrrev_b32_e32 v4, 4, v9
	v_mul_lo_u32 v4, v4, s42
	v_add3_u32 v4, 0, v4, v13
	ds_read_b128 v[4:7], v4
	s_waitcnt lgkmcnt(1)
	buffer_store_dwordx4 v[0:3], v8, s[4:7], 0 offen sc1
	v_add_u32_e32 v12, 0xe00, v12
	v_lshrrev_b32_e32 v8, 4, v12
	v_lshrrev_b32_e32 v0, 4, v15
	v_mul_lo_u32 v0, v0, s42
	v_add3_u32 v0, 0, v0, v13
	v_mul_lo_u32 v8, v8, s42
	ds_read_b128 v[0:3], v0
	v_add3_u32 v8, 0, v8, v13
	v_lshlrev_b32_e32 v14, 4, v9
	ds_read_b128 v[8:11], v8
	s_waitcnt lgkmcnt(2)
	buffer_store_dwordx4 v[4:7], v14, s[4:7], 0 offen sc1
	s_nop 1
	v_lshlrev_b32_e32 v4, 4, v15
	s_waitcnt lgkmcnt(1)
	buffer_store_dwordx4 v[0:3], v4, s[4:7], 0 offen sc1
	s_nop 1
	v_lshlrev_b32_e32 v0, 4, v12
	s_waitcnt lgkmcnt(0)
	buffer_store_dwordx4 v[8:11], v0, s[4:7], 0 offen sc1
	s_add_i32 s4, s87, 0x4000
	s_ashr_i32 s5, s4, 31
	s_barrier
	s_lshl_b64 s[4:5], s[4:5], 2
	s_waitcnt vmcnt(0)
	s_add_u32 s6, s12, s4
	s_addc_u32 s7, s63, s5
	s_and_b64 vcc, exec, s[70:71]
	s_barrier
	s_cbranch_vccnz .LBB0_323
	v_mbcnt_lo_u32_b32 v0, -1, 0
	v_mbcnt_hi_u32_b32 v0, -1, v0
	s_nop 0
	v_cmp_eq_u32_e32 vcc, 0, v0
	s_and_saveexec_b64 s[4:5], vcc
	s_cbranch_execz .LBB0_322
	s_mov_b64 s[42:43], exec
	v_mbcnt_lo_u32_b32 v0, s42, 0
	v_mbcnt_hi_u32_b32 v0, s43, v0
	v_cmp_eq_u32_e32 vcc, 0, v0
	s_and_b64 s[44:45], exec, vcc
	s_mov_b64 exec, s[44:45]
	s_cbranch_execz .LBB0_322
	s_bcnt1_i32_b64 s42, s[42:43]
	v_mov_b32_e32 v0, 0
	v_mov_b32_e32 v1, s42
	global_atomic_add v0, v1, s[6:7]
